# combination on v21: counted waits in the residual epilogues + next unit's K-tile-1 A loads at the loop exit + FFN-up alignment barrier after the row-scale work
# baseline (speedup 1.0000x reference)
.LBB0_981:
	s_bfe_u32 s12, s6, 0x20006
	s_mul_i32 s6, s4, 0x3000
	s_lshl_b32 s4, s4, 11
	s_add_i32 s4, s4, 0
	s_lshl_b32 s7, s5, 10
	v_and_b32_e32 v153, 15, v130
	v_lshrrev_b32_e32 v130, 1, v130
	s_add_i32 s4, s4, s7
	v_and_b32_e32 v151, 24, v130
	v_lshl_add_u32 v130, v153, 6, s4
	v_add_u32_e32 v150, 0x26000, v130
	ds_read_b128 v[130:133], v150
	ds_read_b128 v[134:137], v150 offset:16
	ds_read_b128 v[156:159], v150 offset:32
	ds_read_b128 v[160:163], v150 offset:48
	s_lshl_b32 s4, s5, 2
	s_or_b32 s4, s4, s12
	s_waitcnt lgkmcnt(0)
	v_ffbh_u32_e32 v152, v131
	v_min_u32_e32 v152, 32, v152
	v_lshlrev_b64 v[130:131], v152, v[130:131]
	v_min_u32_e32 v130, 1, v130
	v_or_b32_e32 v130, v131, v130
	v_cvt_f32_u32_e32 v130, v130
	v_sub_u32_e32 v131, 32, v152
	s_mulk_i32 s4, 0x600
	s_add_i32 s5, s6, 0
	v_ldexp_f32 v150, v130, v131
	v_ffbh_u32_e32 v130, v133
	v_min_u32_e32 v152, 32, v130
	v_lshlrev_b64 v[130:131], v152, v[132:133]
	v_min_u32_e32 v130, 1, v130
	v_or_b32_e32 v130, v131, v130
	v_cvt_f32_u32_e32 v130, v130
	v_fmamk_f32 v131, v150, 0x30000000, v1
	v_rsq_f32_e32 v150, v131
	v_sub_u32_e32 v131, 32, v152
	v_ldexp_f32 v132, v130, v131
	v_ffbh_u32_e32 v130, v135
	v_min_u32_e32 v133, 32, v130
	v_lshlrev_b64 v[130:131], v133, v[134:135]
	v_min_u32_e32 v130, 1, v130
	v_or_b32_e32 v130, v131, v130
	v_cvt_f32_u32_e32 v130, v130
	v_fmamk_f32 v131, v132, 0x30000000, v1
	v_rsq_f32_e32 v152, v131
	v_sub_u32_e32 v131, 32, v133
	v_ldexp_f32 v132, v130, v131
	v_ffbh_u32_e32 v130, v137
	v_min_u32_e32 v133, 32, v130
	v_lshlrev_b64 v[130:131], v133, v[136:137]
	v_min_u32_e32 v130, 1, v130
	v_or_b32_e32 v130, v131, v130
	v_cvt_f32_u32_e32 v130, v130
	v_fmamk_f32 v131, v132, 0x30000000, v1
	v_rsq_f32_e32 v154, v131
	v_sub_u32_e32 v131, 32, v133
	v_ldexp_f32 v132, v130, v131
	v_ffbh_u32_e32 v130, v157
	v_min_u32_e32 v133, 32, v130
	v_lshlrev_b64 v[130:131], v133, v[156:157]
	v_min_u32_e32 v130, 1, v130
	v_or_b32_e32 v130, v131, v130
	v_cvt_f32_u32_e32 v130, v130
	v_fmamk_f32 v131, v132, 0x30000000, v1
	v_rsq_f32_e32 v156, v131
	v_sub_u32_e32 v131, 32, v133
	v_ldexp_f32 v132, v130, v131
	v_ffbh_u32_e32 v130, v159
	v_min_u32_e32 v133, 32, v130
	v_lshlrev_b64 v[130:131], v133, v[158:159]
	v_min_u32_e32 v130, 1, v130
	v_or_b32_e32 v130, v131, v130
	v_cvt_f32_u32_e32 v130, v130
	v_fmamk_f32 v131, v132, 0x30000000, v1
	v_rsq_f32_e32 v158, v131
	v_sub_u32_e32 v131, 32, v133
	v_ldexp_f32 v132, v130, v131
	v_ffbh_u32_e32 v130, v161
	v_min_u32_e32 v133, 32, v130
	v_lshlrev_b64 v[130:131], v133, v[160:161]
	v_min_u32_e32 v130, 1, v130
	v_or_b32_e32 v130, v131, v130
	v_cvt_f32_u32_e32 v130, v130
	v_fmamk_f32 v131, v132, 0x30000000, v1
	v_rsq_f32_e32 v160, v131
	v_sub_u32_e32 v131, 32, v133
	v_ldexp_f32 v132, v130, v131
	v_ffbh_u32_e32 v130, v163
	v_min_u32_e32 v133, 32, v130
	v_lshlrev_b64 v[130:131], v133, v[162:163]
	v_min_u32_e32 v130, 1, v130
	v_or_b32_e32 v130, v131, v130
	v_cvt_f32_u32_e32 v130, v130
	v_fmamk_f32 v131, v132, 0x30000000, v1
	v_rsq_f32_e32 v164, v131
	v_sub_u32_e32 v131, 32, v133
	v_ldexp_f32 v130, v130, v131
	v_fmamk_f32 v130, v130, 0x30000000, v1
	s_add_i32 s5, s5, s4
	v_rsq_f32_e32 v162, v130
	v_lshl_add_u32 v130, v151, 2, s5
	v_add_u32_e32 v248, 0x20000, v130
	ds_read2_b64 v[130:133], v248 offset1:16
	ds_read2_b64 v[134:137], v248 offset0:32 offset1:48
	ds_read2_b64 v[236:239], v248 offset0:64 offset1:80
	ds_read2_b64 v[240:243], v248 offset0:96 offset1:112
	v_pk_mul_f32 v[210:211], v[122:123], v[152:153] op_sel_hi:[1,0]
	v_pk_mul_f32 v[204:205], v[110:111], v[152:153] op_sel_hi:[1,0]
	v_pk_mul_f32 v[192:193], v[126:127], v[150:151] op_sel_hi:[1,0]
	v_pk_mul_f32 v[184:185], v[118:119], v[150:151] op_sel_hi:[1,0]
	v_pk_mul_f32 v[218:219], v[114:115], v[154:155] op_sel_hi:[1,0]
	v_pk_mul_f32 v[222:223], v[102:103], v[154:155] op_sel_hi:[1,0]
	v_pk_mul_f32 v[230:231], v[106:107], v[156:157] op_sel_hi:[1,0]
	v_pk_mul_f32 v[228:229], v[98:99], v[156:157] op_sel_hi:[1,0]
	v_pk_mul_f32 v[234:235], v[94:95], v[158:159] op_sel_hi:[1,0]
	v_pk_mul_f32 v[232:233], v[86:87], v[158:159] op_sel_hi:[1,0]
	v_pk_mul_f32 v[174:175], v[90:91], v[160:161] op_sel_hi:[1,0]
	v_pk_mul_f32 v[176:177], v[78:79], v[160:161] op_sel_hi:[1,0]
	v_pk_mul_f32 v[114:115], v[82:83], v[164:165] op_sel_hi:[1,0]
	v_pk_mul_f32 v[70:71], v[70:71], v[164:165] op_sel_hi:[1,0]
	v_pk_mul_f32 v[224:225], v[74:75], v[162:163] op_sel_hi:[1,0]
	v_pk_mul_f32 v[220:221], v[66:67], v[162:163] op_sel_hi:[1,0]
	s_waitcnt lgkmcnt(0)
	v_pk_fma_f32 v[74:75], v[210:211], v[236:237], v[240:241]
	v_pk_fma_f32 v[78:79], v[204:205], v[238:239], v[242:243]
	v_cmp_eq_u32_e64 s[6:7], 0, v153
	v_cmp_ne_u32_e64 s[4:5], 0, v153
	v_mov_b32_dpp v170, v224 row_shr:1 row_mask:0xf bank_mask:0xf bound_ctrl:1
	v_mov_b32_dpp v171, v225 row_shr:1 row_mask:0xf bank_mask:0xf bound_ctrl:1
	v_mov_b32_dpp v186, v114 row_shr:1 row_mask:0xf bank_mask:0xf bound_ctrl:1
	v_mov_b32_dpp v187, v115 row_shr:1 row_mask:0xf bank_mask:0xf bound_ctrl:1
	v_mov_b32_dpp v126, v220 row_shr:1 row_mask:0xf bank_mask:0xf bound_ctrl:1
	v_mov_b32_dpp v127, v221 row_shr:1 row_mask:0xf bank_mask:0xf bound_ctrl:1
	v_mov_b32_dpp v188, v70 row_shr:1 row_mask:0xf bank_mask:0xf bound_ctrl:1
	v_mov_b32_dpp v189, v71 row_shr:1 row_mask:0xf bank_mask:0xf bound_ctrl:1
	s_and_b64 vcc, exec, s[26:27]
	s_cbranch_vccz .Lalign_l7
	s_barrier
.Lalign_l7:
	s_and_b64 vcc, exec, s[0:1]
	v_pk_fma_f32 v[166:167], v[192:193], v[236:237], v[240:241]
	v_pk_fma_f32 v[66:67], v[184:185], v[238:239], v[242:243]
	v_pk_fma_f32 v[180:181], v[218:219], v[236:237], v[240:241]
	v_pk_fma_f32 v[172:173], v[222:223], v[238:239], v[242:243]
	v_pk_fma_f32 v[190:191], v[236:237], v[230:231], v[240:241]
	v_pk_fma_f32 v[182:183], v[228:229], v[238:239], v[242:243]
	v_pk_fma_f32 v[208:209], v[236:237], v[234:235], v[240:241]
	v_pk_fma_f32 v[206:207], v[232:233], v[238:239], v[242:243]
	v_pk_fma_f32 v[216:217], v[236:237], v[174:175], v[240:241]
	v_pk_fma_f32 v[212:213], v[176:177], v[238:239], v[242:243]
	v_pk_fma_f32 v[226:227], v[236:237], v[114:115], v[240:241]
	v_pk_fma_f32 v[214:215], v[70:71], v[238:239], v[242:243]
	v_pk_fma_f32 v[122:123], v[236:237], v[224:225], v[240:241]
	v_pk_fma_f32 v[118:119], v[238:239], v[220:221], v[242:243]
	v_pk_fma_f32 v[178:179], v[192:193], v[134:135], v[74:75]
	v_pk_fma_f32 v[168:169], v[184:185], v[136:137], v[78:79]
	s_cbranch_vccnz .LBB0_983
	v_pk_fma_f32 v[74:75], v[134:135], v[170:171], v[166:167]
	s_mov_b32 s10, 0xbfb8aa3b
	v_pk_fma_f32 v[74:75], v[130:131], v[186:187], v[74:75]
	v_pk_fma_f32 v[78:79], v[136:137], v[126:127], v[66:67]
	v_pk_mul_f32 v[82:83], v[74:75], s[10:11] op_sel_hi:[1,0]
	v_pk_fma_f32 v[78:79], v[132:133], v[188:189], v[78:79]
	v_exp_f32_e32 v82, v82
	v_exp_f32_e32 v83, v83
	s_nop 0
	v_pk_add_f32 v[82:83], v[82:83], 1.0 op_sel_hi:[1,0]
	s_nop 0
	v_rcp_f32_e32 v82, v82
	v_rcp_f32_e32 v83, v83
	s_nop 0
	v_pk_mul_f32 v[74:75], v[74:75], v[82:83]
	s_nop 0
	v_pk_mul_f32 v[86:87], v[78:79], v[74:75]
	v_pk_fma_f32 v[74:75], v[130:131], v[170:171], v[178:179]
	v_pk_fma_f32 v[78:79], v[132:133], v[126:127], v[168:169]
	v_pk_mul_f32 v[82:83], v[74:75], s[10:11] op_sel_hi:[1,0]
	s_nop 0
	v_exp_f32_e32 v82, v82
	v_exp_f32_e32 v83, v83
	s_nop 0
	v_pk_add_f32 v[82:83], v[82:83], 1.0 op_sel_hi:[1,0]
	s_nop 0
	v_rcp_f32_e32 v82, v82
	v_rcp_f32_e32 v83, v83
	s_nop 0
	v_pk_mul_f32 v[74:75], v[74:75], v[82:83]
	s_nop 0
	v_pk_mul_f32 v[98:99], v[78:79], v[74:75]
	v_pk_fma_f32 v[74:75], v[210:211], v[134:135], v[180:181]
	v_pk_fma_f32 v[78:79], v[204:205], v[136:137], v[172:173]
	v_pk_fma_f32 v[74:75], v[192:193], v[130:131], v[74:75]
	v_pk_fma_f32 v[78:79], v[184:185], v[132:133], v[78:79]
	v_pk_mul_f32 v[82:83], v[74:75], s[10:11] op_sel_hi:[1,0]
	s_nop 0
	v_exp_f32_e32 v82, v82
	v_exp_f32_e32 v83, v83
	s_nop 0
	v_pk_add_f32 v[82:83], v[82:83], 1.0 op_sel_hi:[1,0]
	s_nop 0
	v_rcp_f32_e32 v82, v82
	v_rcp_f32_e32 v83, v83
	s_nop 0
	v_pk_mul_f32 v[74:75], v[74:75], v[82:83]
	s_nop 0
	v_pk_mul_f32 v[78:79], v[78:79], v[74:75]
	v_pk_fma_f32 v[74:75], v[134:135], v[218:219], v[190:191]
	v_pk_fma_f32 v[82:83], v[222:223], v[136:137], v[182:183]
	v_pk_fma_f32 v[74:75], v[130:131], v[210:211], v[74:75]
	v_pk_fma_f32 v[82:83], v[204:205], v[132:133], v[82:83]
	v_pk_mul_f32 v[90:91], v[74:75], s[10:11] op_sel_hi:[1,0]
	s_nop 0
	v_exp_f32_e32 v90, v90
	v_exp_f32_e32 v91, v91
	s_nop 0
	v_pk_add_f32 v[90:91], v[90:91], 1.0 op_sel_hi:[1,0]
	s_nop 0
	v_rcp_f32_e32 v90, v90
	v_rcp_f32_e32 v91, v91
	s_nop 0
	v_pk_mul_f32 v[74:75], v[74:75], v[90:91]
	s_nop 0
	v_pk_mul_f32 v[82:83], v[82:83], v[74:75]
	v_pk_fma_f32 v[74:75], v[134:135], v[230:231], v[208:209]
	v_pk_fma_f32 v[90:91], v[228:229], v[136:137], v[206:207]
	v_pk_fma_f32 v[74:75], v[130:131], v[218:219], v[74:75]
	v_pk_fma_f32 v[90:91], v[222:223], v[132:133], v[90:91]
	v_pk_mul_f32 v[94:95], v[74:75], s[10:11] op_sel_hi:[1,0]
	s_nop 0
	v_exp_f32_e32 v94, v94
	v_exp_f32_e32 v95, v95
	s_nop 0
	v_pk_add_f32 v[94:95], v[94:95], 1.0 op_sel_hi:[1,0]
	s_nop 0
	v_rcp_f32_e32 v94, v94
	v_rcp_f32_e32 v95, v95
	s_nop 0
	v_pk_mul_f32 v[74:75], v[74:75], v[94:95]
	s_nop 0
	v_pk_mul_f32 v[90:91], v[90:91], v[74:75]
	v_pk_fma_f32 v[74:75], v[134:135], v[234:235], v[216:217]
	v_pk_fma_f32 v[94:95], v[232:233], v[136:137], v[212:213]
	v_pk_fma_f32 v[74:75], v[130:131], v[230:231], v[74:75]
	v_pk_fma_f32 v[94:95], v[228:229], v[132:133], v[94:95]
	v_pk_mul_f32 v[102:103], v[74:75], s[10:11] op_sel_hi:[1,0]
	s_nop 0
	v_exp_f32_e32 v102, v102
	v_exp_f32_e32 v103, v103
	s_nop 0
	v_pk_add_f32 v[102:103], v[102:103], 1.0 op_sel_hi:[1,0]
	s_nop 0
	v_rcp_f32_e32 v102, v102
	v_rcp_f32_e32 v103, v103
	s_nop 0
	v_pk_mul_f32 v[74:75], v[74:75], v[102:103]
	s_nop 0
	v_pk_mul_f32 v[94:95], v[94:95], v[74:75]
	v_pk_fma_f32 v[74:75], v[134:135], v[174:175], v[226:227]
	v_pk_fma_f32 v[102:103], v[176:177], v[136:137], v[214:215]
	v_pk_fma_f32 v[74:75], v[130:131], v[234:235], v[74:75]
	v_pk_fma_f32 v[102:103], v[232:233], v[132:133], v[102:103]
	v_pk_mul_f32 v[106:107], v[74:75], s[10:11] op_sel_hi:[1,0]
	s_mov_b64 s[10:11], 0
	v_exp_f32_e32 v106, v106
	v_exp_f32_e32 v107, v107
	s_nop 0
	v_pk_add_f32 v[106:107], v[106:107], 1.0 op_sel_hi:[1,0]
	s_nop 0
	v_rcp_f32_e32 v106, v106
	v_rcp_f32_e32 v107, v107
	s_nop 0
	v_pk_mul_f32 v[74:75], v[74:75], v[106:107]
	s_nop 0
	v_pk_mul_f32 v[102:103], v[102:103], v[74:75]
	v_pk_fma_f32 v[74:75], v[134:135], v[114:115], v[122:123]
	s_nop 0
	v_pk_fma_f32 v[106:107], v[130:131], v[174:175], v[74:75]
	v_pk_fma_f32 v[74:75], v[136:137], v[70:71], v[118:119]
	s_nop 0
	v_pk_fma_f32 v[110:111], v[132:133], v[176:177], v[74:75]
